# P6 and P7 GEMM epilogues rewritten: LDS-staged row-contiguous stores, and gate / partial / residual loads issued up front as coalesced dwordx4 instead of a serialized load-wait-store ladder
# speedup vs baseline: 1.0831x; 1.0329x over previous
; __device__ __forceinline__ unsigned pk2(float lo, float hi) { f32v2_t v = {lo, hi}; bf16v2_t r = __builtin_convertvector(v, bf16v2_t); return __builtin_bit_cast(unsigned, r); }
; __device__ __forceinline__ float bflo(unsigned w) { return __uint_as_float(w << 16); }
; __device__ __forceinline__ float bfhi(unsigned w) { return __uint_as_float(w & 0xffff0000u); }
; __device__ void phase_merge(const Params& p, char* lds) {
;     ...
;     {
;       f32x16 acc[2][2]; zero_acc(acc);
;       gemm_mainloop<true>((const bf16_t*)(ws + W_B) + (size_t)m0 * LDH, LDH, (const bf16_t*)(ws + W_WB) + (size_t)n0 * LDH, LDH, 1024, acc, lds, 2 * ((mt + nt) & 7));
;       int l31b = l31; asm volatile("" : "+v"(l31b));
; #pragma unroll
;       for (int i = 0; i < 2; ++i)
; #pragma unroll
;         for (int j = 0; j < 2; ++j) {
;           const int tok = m0 + wr * 64 + i * 32 + l31b; const int cb = n0 + wc * 64 + j * 32;
;           const bf16_t* gp = gates + (size_t)tok * 2048 + 1024 + cb + 4 * hh;
;           bf16_t* op = mg + (size_t)tok * LDH + cb + 4 * hh;
; #pragma unroll
;           for (int g = 0; g < 4; ++g) {
;             const u32x2 gv = *(const u32x2*)(gp + 8 * g);
;             const u32x2 pv = *(const u32x2*)(op + 8 * g);
;             u32x2 w;
;             w.x = pk2(bflo(pv.x) + acc[i][j][4 * g] * bflo(gv.x), bfhi(pv.x) + acc[i][j][4 * g + 1] * bfhi(gv.x));
;             w.y = pk2(bflo(pv.y) + acc[i][j][4 * g + 2] * bflo(gv.y), bfhi(pv.y) + acc[i][j][4 * g + 3] * bfhi(gv.y));
;             *(u32x2*)(op + 8 * g) = w;
;           }
;         }
.LBB0_787:
	s_add_i32 s2, s2, 1
	v_and_b32_e32 v123, 63, v181
	v_lshrrev_b32_e32 v122, 6, v181
	v_and_b32_e32 v118, 31, v123
	v_lshrrev_b32_e32 v119, 5, v123
	v_mul_u32_u24_e32 v118, 0x110, v118
	v_lshlrev_b32_e32 v119, 4, v119
	v_mul_u32_u24_e32 v120, 0x2200, v122
	v_add3_u32 v118, v118, v119, v120
	v_add_u32_e32 v118, 0x8000, v118
	v_add_u32_e32 v119, 0x8000, v120
	v_lshrrev_b32_e32 v120, 3, v123
	v_and_b32_e32 v121, 7, v123
	v_mul_u32_u24_e32 v123, 0x110, v120
	v_add_u32_e32 v119, v119, v123
	v_lshl_add_u32 v119, v121, 5, v119
	v_readlane_b32 vcc_lo, v248, 4
	v_readlane_b32 vcc_hi, v248, 5
	s_lshl_b32 s0, s3, 12
	s_lshl_b32 s1, s44, 1
	s_add_i32 s0, s0, s1
	s_mul_i32 s10, s3, 0x880
	s_add_i32 s1, s1, s10
	s_add_i32 s1, s1, 0x1699e000
	v_lshrrev_b32_e32 v124, 1, v122
	v_mul_u32_u24_e32 v124, 0x40000, v124
	v_mul_u32_u24_e32 v126, 0x1000, v120
	v_add_u32_e32 v124, v124, v126
	v_and_b32_e32 v126, 1, v122
	v_mul_u32_u24_e32 v126, 0x80, v126
	v_lshl_add_u32 v126, v121, 4, v126
	v_add3_u32 v124, v124, v126, s0
	v_lshrrev_b32_e32 v125, 1, v122
	v_mul_u32_u24_e32 v125, 0x22000, v125
	v_mul_u32_u24_e32 v126, 0x880, v120
	v_add_u32_e32 v125, v125, v126
	v_and_b32_e32 v126, 1, v122
	v_mul_u32_u24_e32 v126, 0x80, v126
	v_lshl_add_u32 v126, v121, 4, v126
	v_add3_u32 v125, v125, v126, s1
	ds_write_b128 v118, v[48:51] offset:0
	ds_write_b128 v118, v[52:55] offset:32
	ds_write_b128 v118, v[56:59] offset:64
	ds_write_b128 v118, v[60:63] offset:96
	ds_write_b128 v118, v[32:35] offset:128
	ds_write_b128 v118, v[36:39] offset:160
	ds_write_b128 v118, v[40:43] offset:192
	ds_write_b128 v118, v[44:47] offset:224
	s_waitcnt lgkmcnt(0)
	global_load_dwordx4 v[84:87], v124, vcc offset:2048
	v_add_u32_e32 v124, 0x8000, v124
	global_load_dwordx4 v[88:91], v124, vcc offset:2048
	v_add_u32_e32 v124, 0x8000, v124
	global_load_dwordx4 v[92:95], v124, vcc offset:2048
	v_add_u32_e32 v124, 0x8000, v124
	global_load_dwordx4 v[96:99], v124, vcc offset:2048
	v_add_u32_e32 v124, 0x8000, v124
	v_mov_b32_e32 v126, v125
	global_load_dwordx4 v[48:51], v126, s[96:97]
	v_add_u32_e32 v126, 0x4400, v126
	global_load_dwordx4 v[52:55], v126, s[96:97]
	v_add_u32_e32 v126, 0x4400, v126
	global_load_dwordx4 v[56:59], v126, s[96:97]
	v_add_u32_e32 v126, 0x4400, v126
	global_load_dwordx4 v[60:63], v126, s[96:97]
	v_add_u32_e32 v126, 0x4400, v126
	ds_read_b128 v[32:35], v119 offset:0
	ds_read_b128 v[36:39], v119 offset:16
	ds_read_b128 v[40:43], v119 offset:2176
	ds_read_b128 v[44:47], v119 offset:2192
	s_waitcnt vmcnt(3) lgkmcnt(2)
	v_lshlrev_b32_e32 v127, 16, v84
	v_lshlrev_b32_e32 v128, 16, v48
	v_fma_f32 v32, v32, v127, v128
	v_and_b32_e32 v127, 0xffff0000, v84
	v_and_b32_e32 v128, 0xffff0000, v48
	v_fma_f32 v33, v33, v127, v128
	v_lshlrev_b32_e32 v127, 16, v85
	v_lshlrev_b32_e32 v128, 16, v49
	v_fma_f32 v34, v34, v127, v128
	v_and_b32_e32 v127, 0xffff0000, v85
	v_and_b32_e32 v128, 0xffff0000, v49
	v_fma_f32 v35, v35, v127, v128
	v_lshlrev_b32_e32 v127, 16, v86
	v_lshlrev_b32_e32 v128, 16, v50
	v_fma_f32 v36, v36, v127, v128
	v_and_b32_e32 v127, 0xffff0000, v86
	v_and_b32_e32 v128, 0xffff0000, v50
	v_fma_f32 v37, v37, v127, v128
	v_lshlrev_b32_e32 v127, 16, v87
	v_lshlrev_b32_e32 v128, 16, v51
	v_fma_f32 v38, v38, v127, v128
	v_and_b32_e32 v127, 0xffff0000, v87
	v_and_b32_e32 v128, 0xffff0000, v51
	v_fma_f32 v39, v39, v127, v128
	v_cvt_pk_bf16_f32 v32, v32, v33
	v_cvt_pk_bf16_f32 v33, v34, v35
	v_cvt_pk_bf16_f32 v34, v36, v37
	v_cvt_pk_bf16_f32 v35, v38, v39
	global_store_dwordx4 v125, v[32:35], s[96:97]
	v_add_u32_e32 v125, 0x4400, v125
	s_waitcnt vmcnt(3) lgkmcnt(0)
	v_lshlrev_b32_e32 v127, 16, v88
	v_lshlrev_b32_e32 v128, 16, v52
	v_fma_f32 v40, v40, v127, v128
	v_and_b32_e32 v127, 0xffff0000, v88
	v_and_b32_e32 v128, 0xffff0000, v52
	v_fma_f32 v41, v41, v127, v128
	v_lshlrev_b32_e32 v127, 16, v89
	v_lshlrev_b32_e32 v128, 16, v53
	v_fma_f32 v42, v42, v127, v128
	v_and_b32_e32 v127, 0xffff0000, v89
	v_and_b32_e32 v128, 0xffff0000, v53
	v_fma_f32 v43, v43, v127, v128
	v_lshlrev_b32_e32 v127, 16, v90
	v_lshlrev_b32_e32 v128, 16, v54
	v_fma_f32 v44, v44, v127, v128
	v_and_b32_e32 v127, 0xffff0000, v90
	v_and_b32_e32 v128, 0xffff0000, v54
	v_fma_f32 v45, v45, v127, v128
	v_lshlrev_b32_e32 v127, 16, v91
	v_lshlrev_b32_e32 v128, 16, v55
	v_fma_f32 v46, v46, v127, v128
	v_and_b32_e32 v127, 0xffff0000, v91
	v_and_b32_e32 v128, 0xffff0000, v55
	v_fma_f32 v47, v47, v127, v128
	v_cvt_pk_bf16_f32 v40, v40, v41
	v_cvt_pk_bf16_f32 v41, v42, v43
	v_cvt_pk_bf16_f32 v42, v44, v45
	v_cvt_pk_bf16_f32 v43, v46, v47
	global_store_dwordx4 v125, v[40:43], s[96:97]
	v_add_u32_e32 v125, 0x4400, v125
	ds_read_b128 v[32:35], v119 offset:4352
	ds_read_b128 v[36:39], v119 offset:4368
	ds_read_b128 v[40:43], v119 offset:6528
	ds_read_b128 v[44:47], v119 offset:6544
	s_waitcnt vmcnt(3) lgkmcnt(2)
	v_lshlrev_b32_e32 v127, 16, v92
	v_lshlrev_b32_e32 v128, 16, v56
	v_fma_f32 v32, v32, v127, v128
	v_and_b32_e32 v127, 0xffff0000, v92
	v_and_b32_e32 v128, 0xffff0000, v56
	v_fma_f32 v33, v33, v127, v128
	v_lshlrev_b32_e32 v127, 16, v93
	v_lshlrev_b32_e32 v128, 16, v57
	v_fma_f32 v34, v34, v127, v128
	v_and_b32_e32 v127, 0xffff0000, v93
	v_and_b32_e32 v128, 0xffff0000, v57
	v_fma_f32 v35, v35, v127, v128
	v_lshlrev_b32_e32 v127, 16, v94
	v_lshlrev_b32_e32 v128, 16, v58
	v_fma_f32 v36, v36, v127, v128
	v_and_b32_e32 v127, 0xffff0000, v94
	v_and_b32_e32 v128, 0xffff0000, v58
	v_fma_f32 v37, v37, v127, v128
	v_lshlrev_b32_e32 v127, 16, v95
	v_lshlrev_b32_e32 v128, 16, v59
	v_fma_f32 v38, v38, v127, v128
	v_and_b32_e32 v127, 0xffff0000, v95
	v_and_b32_e32 v128, 0xffff0000, v59
	v_fma_f32 v39, v39, v127, v128
	v_cvt_pk_bf16_f32 v32, v32, v33
	v_cvt_pk_bf16_f32 v33, v34, v35
	v_cvt_pk_bf16_f32 v34, v36, v37
	v_cvt_pk_bf16_f32 v35, v38, v39
	global_store_dwordx4 v125, v[32:35], s[96:97]
	v_add_u32_e32 v125, 0x4400, v125
	s_waitcnt vmcnt(3) lgkmcnt(0)
; __device__ __forceinline__ unsigned pk2(float lo, float hi) { f32v2_t v = {lo, hi}; bf16v2_t r = __builtin_convertvector(v, bf16v2_t); return __builtin_bit_cast(unsigned, r); }
; __device__ __forceinline__ float bflo(unsigned w) { return __uint_as_float(w << 16); }
; __device__ __forceinline__ float bfhi(unsigned w) { return __uint_as_float(w & 0xffff0000u); }
; __device__ void phase_merge(const Params& p, char* lds) {
;     ...
; #pragma unroll
;       for (int i = 0; i < 2; ++i)
; #pragma unroll
;         for (int j = 0; j < 2; ++j) {
;           const int tok = m0 + wr * 64 + i * 32 + l31b; const int cb = n0 + wc * 64 + j * 32;
;           const bf16_t* gp = gates + (size_t)tok * 2048 + 1024 + cb + 4 * hh;
;           bf16_t* op = mg + (size_t)tok * LDH + cb + 4 * hh;
; #pragma unroll
;           for (int g = 0; g < 4; ++g) {
;             const u32x2 gv = *(const u32x2*)(gp + 8 * g);
;             const u32x2 pv = *(const u32x2*)(op + 8 * g);
;             u32x2 w;
;             w.x = pk2(bflo(pv.x) + acc[i][j][4 * g] * bflo(gv.x), bfhi(pv.x) + acc[i][j][4 * g + 1] * bfhi(gv.x));
;             w.y = pk2(bflo(pv.y) + acc[i][j][4 * g + 2] * bflo(gv.y), bfhi(pv.y) + acc[i][j][4 * g + 3] * bfhi(gv.y));
;             *(u32x2*)(op + 8 * g) = w;
;           }
;         }
	v_lshlrev_b32_e32 v127, 16, v96
	v_lshlrev_b32_e32 v128, 16, v60
	v_fma_f32 v40, v40, v127, v128
	v_and_b32_e32 v127, 0xffff0000, v96
	v_and_b32_e32 v128, 0xffff0000, v60
	v_fma_f32 v41, v41, v127, v128
	v_lshlrev_b32_e32 v127, 16, v97
	v_lshlrev_b32_e32 v128, 16, v61
	v_fma_f32 v42, v42, v127, v128
	v_and_b32_e32 v127, 0xffff0000, v97
	v_and_b32_e32 v128, 0xffff0000, v61
	v_fma_f32 v43, v43, v127, v128
	v_lshlrev_b32_e32 v127, 16, v98
	v_lshlrev_b32_e32 v128, 16, v62
	v_fma_f32 v44, v44, v127, v128
	v_and_b32_e32 v127, 0xffff0000, v98
	v_and_b32_e32 v128, 0xffff0000, v62
	v_fma_f32 v45, v45, v127, v128
	v_lshlrev_b32_e32 v127, 16, v99
	v_lshlrev_b32_e32 v128, 16, v63
	v_fma_f32 v46, v46, v127, v128
	v_and_b32_e32 v127, 0xffff0000, v99
	v_and_b32_e32 v128, 0xffff0000, v63
	v_fma_f32 v47, v47, v127, v128
	v_cvt_pk_bf16_f32 v40, v40, v41
	v_cvt_pk_bf16_f32 v41, v42, v43
	v_cvt_pk_bf16_f32 v42, v44, v45
	v_cvt_pk_bf16_f32 v43, v46, v47
	global_store_dwordx4 v125, v[40:43], s[96:97]
	v_add_u32_e32 v125, 0x4400, v125
	ds_write_b128 v118, v[16:19] offset:0
	ds_write_b128 v118, v[20:23] offset:32
	ds_write_b128 v118, v[24:27] offset:64
	ds_write_b128 v118, v[28:31] offset:96
	ds_write_b128 v118, v[0:3] offset:128
	ds_write_b128 v118, v[4:7] offset:160
	ds_write_b128 v118, v[8:11] offset:192
	ds_write_b128 v118, v[12:15] offset:224
	s_waitcnt lgkmcnt(0)
	global_load_dwordx4 v[84:87], v124, vcc offset:2048
	v_add_u32_e32 v124, 0x8000, v124
	global_load_dwordx4 v[88:91], v124, vcc offset:2048
	v_add_u32_e32 v124, 0x8000, v124
	global_load_dwordx4 v[92:95], v124, vcc offset:2048
	v_add_u32_e32 v124, 0x8000, v124
	global_load_dwordx4 v[96:99], v124, vcc offset:2048
	v_add_u32_e32 v124, 0x8000, v124
	v_mov_b32_e32 v126, v125
	global_load_dwordx4 v[16:19], v126, s[96:97]
	v_add_u32_e32 v126, 0x4400, v126
	global_load_dwordx4 v[20:23], v126, s[96:97]
	v_add_u32_e32 v126, 0x4400, v126
	global_load_dwordx4 v[24:27], v126, s[96:97]
	v_add_u32_e32 v126, 0x4400, v126
	global_load_dwordx4 v[28:31], v126, s[96:97]
	v_add_u32_e32 v126, 0x4400, v126
	ds_read_b128 v[0:3], v119 offset:0
	ds_read_b128 v[4:7], v119 offset:16
	ds_read_b128 v[8:11], v119 offset:2176
	ds_read_b128 v[12:15], v119 offset:2192
	s_waitcnt vmcnt(3) lgkmcnt(2)
	v_lshlrev_b32_e32 v127, 16, v84
	v_lshlrev_b32_e32 v128, 16, v16
	v_fma_f32 v0, v0, v127, v128
	v_and_b32_e32 v127, 0xffff0000, v84
	v_and_b32_e32 v128, 0xffff0000, v16
	v_fma_f32 v1, v1, v127, v128
	v_lshlrev_b32_e32 v127, 16, v85
	v_lshlrev_b32_e32 v128, 16, v17
	v_fma_f32 v2, v2, v127, v128
	v_and_b32_e32 v127, 0xffff0000, v85
	v_and_b32_e32 v128, 0xffff0000, v17
	v_fma_f32 v3, v3, v127, v128
	v_lshlrev_b32_e32 v127, 16, v86
	v_lshlrev_b32_e32 v128, 16, v18
	v_fma_f32 v4, v4, v127, v128
	v_and_b32_e32 v127, 0xffff0000, v86
	v_and_b32_e32 v128, 0xffff0000, v18
	v_fma_f32 v5, v5, v127, v128
	v_lshlrev_b32_e32 v127, 16, v87
	v_lshlrev_b32_e32 v128, 16, v19
	v_fma_f32 v6, v6, v127, v128
	v_and_b32_e32 v127, 0xffff0000, v87
	v_and_b32_e32 v128, 0xffff0000, v19
	v_fma_f32 v7, v7, v127, v128
	v_cvt_pk_bf16_f32 v0, v0, v1
	v_cvt_pk_bf16_f32 v1, v2, v3
	v_cvt_pk_bf16_f32 v2, v4, v5
	v_cvt_pk_bf16_f32 v3, v6, v7
	global_store_dwordx4 v125, v[0:3], s[96:97]
	v_add_u32_e32 v125, 0x4400, v125
	s_waitcnt vmcnt(3) lgkmcnt(0)
	v_lshlrev_b32_e32 v127, 16, v88
	v_lshlrev_b32_e32 v128, 16, v20
	v_fma_f32 v8, v8, v127, v128
	v_and_b32_e32 v127, 0xffff0000, v88
	v_and_b32_e32 v128, 0xffff0000, v20
	v_fma_f32 v9, v9, v127, v128
	v_lshlrev_b32_e32 v127, 16, v89
	v_lshlrev_b32_e32 v128, 16, v21
	v_fma_f32 v10, v10, v127, v128
	v_and_b32_e32 v127, 0xffff0000, v89
	v_and_b32_e32 v128, 0xffff0000, v21
	v_fma_f32 v11, v11, v127, v128
	v_lshlrev_b32_e32 v127, 16, v90
	v_lshlrev_b32_e32 v128, 16, v22
	v_fma_f32 v12, v12, v127, v128
	v_and_b32_e32 v127, 0xffff0000, v90
	v_and_b32_e32 v128, 0xffff0000, v22
	v_fma_f32 v13, v13, v127, v128
	v_lshlrev_b32_e32 v127, 16, v91
	v_lshlrev_b32_e32 v128, 16, v23
	v_fma_f32 v14, v14, v127, v128
	v_and_b32_e32 v127, 0xffff0000, v91
	v_and_b32_e32 v128, 0xffff0000, v23
	v_fma_f32 v15, v15, v127, v128
	v_cvt_pk_bf16_f32 v8, v8, v9
	v_cvt_pk_bf16_f32 v9, v10, v11
	v_cvt_pk_bf16_f32 v10, v12, v13
	v_cvt_pk_bf16_f32 v11, v14, v15
	global_store_dwordx4 v125, v[8:11], s[96:97]
	v_add_u32_e32 v125, 0x4400, v125
	ds_read_b128 v[0:3], v119 offset:4352
	ds_read_b128 v[4:7], v119 offset:4368
	ds_read_b128 v[8:11], v119 offset:6528
	ds_read_b128 v[12:15], v119 offset:6544
	s_waitcnt vmcnt(3) lgkmcnt(2)
	v_lshlrev_b32_e32 v127, 16, v92
	v_lshlrev_b32_e32 v128, 16, v24
	v_fma_f32 v0, v0, v127, v128
	v_and_b32_e32 v127, 0xffff0000, v92
	v_and_b32_e32 v128, 0xffff0000, v24
	v_fma_f32 v1, v1, v127, v128
	v_lshlrev_b32_e32 v127, 16, v93
	v_lshlrev_b32_e32 v128, 16, v25
	v_fma_f32 v2, v2, v127, v128
	v_and_b32_e32 v127, 0xffff0000, v93
	v_and_b32_e32 v128, 0xffff0000, v25
	v_fma_f32 v3, v3, v127, v128
	v_lshlrev_b32_e32 v127, 16, v94
	v_lshlrev_b32_e32 v128, 16, v26
	v_fma_f32 v4, v4, v127, v128
	v_and_b32_e32 v127, 0xffff0000, v94
	v_and_b32_e32 v128, 0xffff0000, v26
	v_fma_f32 v5, v5, v127, v128
	v_lshlrev_b32_e32 v127, 16, v95
	v_lshlrev_b32_e32 v128, 16, v27
	v_fma_f32 v6, v6, v127, v128
	v_and_b32_e32 v127, 0xffff0000, v95
	v_and_b32_e32 v128, 0xffff0000, v27
	v_fma_f32 v7, v7, v127, v128
	v_cvt_pk_bf16_f32 v0, v0, v1
	v_cvt_pk_bf16_f32 v1, v2, v3
	v_cvt_pk_bf16_f32 v2, v4, v5
	v_cvt_pk_bf16_f32 v3, v6, v7
	global_store_dwordx4 v125, v[0:3], s[96:97]
	v_add_u32_e32 v125, 0x4400, v125
	s_waitcnt vmcnt(3) lgkmcnt(0)
	v_lshlrev_b32_e32 v127, 16, v96
	v_lshlrev_b32_e32 v128, 16, v28
	v_fma_f32 v8, v8, v127, v128
	v_and_b32_e32 v127, 0xffff0000, v96
	v_and_b32_e32 v128, 0xffff0000, v28
	v_fma_f32 v9, v9, v127, v128
	v_lshlrev_b32_e32 v127, 16, v97
	v_lshlrev_b32_e32 v128, 16, v29
	v_fma_f32 v10, v10, v127, v128
	v_and_b32_e32 v127, 0xffff0000, v97
	v_and_b32_e32 v128, 0xffff0000, v29
	v_fma_f32 v11, v11, v127, v128
	v_lshlrev_b32_e32 v127, 16, v98
	v_lshlrev_b32_e32 v128, 16, v30
	v_fma_f32 v12, v12, v127, v128
	v_and_b32_e32 v127, 0xffff0000, v98
	v_and_b32_e32 v128, 0xffff0000, v30
	v_fma_f32 v13, v13, v127, v128
	v_lshlrev_b32_e32 v127, 16, v99
	v_lshlrev_b32_e32 v128, 16, v31
	v_fma_f32 v14, v14, v127, v128
	v_and_b32_e32 v127, 0xffff0000, v99
	v_and_b32_e32 v128, 0xffff0000, v31
	v_fma_f32 v15, v15, v127, v128
	v_cvt_pk_bf16_f32 v8, v8, v9
	v_cvt_pk_bf16_f32 v9, v10, v11
	v_cvt_pk_bf16_f32 v10, v12, v13
	v_cvt_pk_bf16_f32 v11, v14, v15
	global_store_dwordx4 v125, v[8:11], s[96:97]
	v_add_u32_e32 v125, 0x4400, v125
	s_mul_i32 s0, s2, s12
	s_add_i32 s0, s0, s33
	s_cmp_lt_i32 s0, s17
	s_cbranch_scc0 .LBB0_800

; __device__ __forceinline__ unsigned pk2(float lo, float hi) { f32v2_t v = {lo, hi}; bf16v2_t r = __builtin_convertvector(v, bf16v2_t); return __builtin_bit_cast(unsigned, r); }
; __device__ __forceinline__ float bflo(unsigned w) { return __uint_as_float(w << 16); }
; __device__ __forceinline__ float bfhi(unsigned w) { return __uint_as_float(w & 0xffff0000u); }
; __device__ void phase_merge(const Params& p, char* lds) {
;     ...
;     {
;       f32x16 acc[2][2]; zero_acc(acc);
;       gemm_mainloop<true>((const bf16_t*)(ws + W_C) + (size_t)m0 * LDH, LDH, (const bf16_t*)(ws + W_WA) + (size_t)n0 * LDH, LDH, 1024, acc, lds, 2 * ((mt + nt) & 7));
; #pragma unroll
;       for (int i = 0; i < 2; ++i)
; #pragma unroll
;         for (int j = 0; j < 2; ++j) {
;           const int tok = m0 + wr * 64 + i * 32 + l31; const int cb = n0 + wc * 64 + j * 32;
;           const bf16_t* gp = gates + (size_t)tok * 2048 + cb + 4 * hh;
;           bf16_t* op = mg + (size_t)tok * LDH + cb + 4 * hh;
; #pragma unroll
;           for (int g = 0; g < 4; ++g) {
;             const u32x2 gv = *(const u32x2*)(gp + 8 * g);
;             u32x2 w;
;             w.x = pk2(acc[i][j][4 * g] * bflo(gv.x), acc[i][j][4 * g + 1] * bfhi(gv.x));
;             w.y = pk2(acc[i][j][4 * g + 2] * bflo(gv.y), acc[i][j][4 * g + 3] * bfhi(gv.y));
;             *(u32x2*)(op + 8 * g) = w;
;           }
;         }
.LBB0_794:
	v_and_b32_e32 v123, 63, v181
	v_lshrrev_b32_e32 v122, 6, v181
	v_and_b32_e32 v118, 31, v123
	v_lshrrev_b32_e32 v119, 5, v123
	v_mul_u32_u24_e32 v118, 0x110, v118
	v_lshlrev_b32_e32 v119, 4, v119
	v_mul_u32_u24_e32 v120, 0x2200, v122
	v_add3_u32 v118, v118, v119, v120
	v_add_u32_e32 v118, 0x8000, v118
	v_add_u32_e32 v119, 0x8000, v120
	v_lshrrev_b32_e32 v120, 3, v123
	v_and_b32_e32 v121, 7, v123
	v_mul_u32_u24_e32 v123, 0x110, v120
	v_add_u32_e32 v119, v119, v123
	v_lshl_add_u32 v119, v121, 5, v119
	v_readlane_b32 vcc_lo, v248, 4
	v_readlane_b32 vcc_hi, v248, 5
	s_lshl_b32 s0, s3, 12
	s_lshl_b32 s1, s44, 1
	s_add_i32 s0, s0, s1
	s_mul_i32 s10, s3, 0x880
	s_add_i32 s1, s1, s10
	s_add_i32 s1, s1, 0x1699e000
	v_lshrrev_b32_e32 v124, 1, v122
	v_mul_u32_u24_e32 v124, 0x40000, v124
	v_mul_u32_u24_e32 v126, 0x1000, v120
	v_add_u32_e32 v124, v124, v126
	v_and_b32_e32 v126, 1, v122
	v_mul_u32_u24_e32 v126, 0x80, v126
	v_lshl_add_u32 v126, v121, 4, v126
	v_add3_u32 v124, v124, v126, s0
	v_lshrrev_b32_e32 v125, 1, v122
	v_mul_u32_u24_e32 v125, 0x22000, v125
	v_mul_u32_u24_e32 v126, 0x880, v120
	v_add_u32_e32 v125, v125, v126
	v_and_b32_e32 v126, 1, v122
	v_mul_u32_u24_e32 v126, 0x80, v126
	v_lshl_add_u32 v126, v121, 4, v126
	v_add3_u32 v125, v125, v126, s1
	ds_write_b128 v118, v[48:51] offset:0
	ds_write_b128 v118, v[52:55] offset:32
	ds_write_b128 v118, v[56:59] offset:64
	ds_write_b128 v118, v[60:63] offset:96
	ds_write_b128 v118, v[32:35] offset:128
	ds_write_b128 v118, v[36:39] offset:160
	ds_write_b128 v118, v[40:43] offset:192
	ds_write_b128 v118, v[44:47] offset:224
	s_waitcnt lgkmcnt(0)
	global_load_dwordx4 v[84:87], v124, vcc offset:0
	v_add_u32_e32 v124, 0x8000, v124
	global_load_dwordx4 v[88:91], v124, vcc offset:0
	v_add_u32_e32 v124, 0x8000, v124
	global_load_dwordx4 v[92:95], v124, vcc offset:0
	v_add_u32_e32 v124, 0x8000, v124
	global_load_dwordx4 v[96:99], v124, vcc offset:0
	v_add_u32_e32 v124, 0x8000, v124
	ds_read_b128 v[32:35], v119 offset:0
	ds_read_b128 v[36:39], v119 offset:16
	ds_read_b128 v[40:43], v119 offset:2176
	ds_read_b128 v[44:47], v119 offset:2192
	s_waitcnt vmcnt(3) lgkmcnt(2)
	v_lshlrev_b32_e32 v127, 16, v84
	v_mul_f32_e32 v32, v32, v127
	v_and_b32_e32 v127, 0xffff0000, v84
	v_mul_f32_e32 v33, v33, v127
	v_lshlrev_b32_e32 v127, 16, v85
	v_mul_f32_e32 v34, v34, v127
	v_and_b32_e32 v127, 0xffff0000, v85
	v_mul_f32_e32 v35, v35, v127
	v_lshlrev_b32_e32 v127, 16, v86
	v_mul_f32_e32 v36, v36, v127
	v_and_b32_e32 v127, 0xffff0000, v86
	v_mul_f32_e32 v37, v37, v127
	v_lshlrev_b32_e32 v127, 16, v87
	v_mul_f32_e32 v38, v38, v127
	v_and_b32_e32 v127, 0xffff0000, v87
	v_mul_f32_e32 v39, v39, v127
	v_cvt_pk_bf16_f32 v32, v32, v33
	v_cvt_pk_bf16_f32 v33, v34, v35
	v_cvt_pk_bf16_f32 v34, v36, v37
	v_cvt_pk_bf16_f32 v35, v38, v39
	global_store_dwordx4 v125, v[32:35], s[96:97]
	v_add_u32_e32 v125, 0x4400, v125
	s_waitcnt vmcnt(3) lgkmcnt(0)
	v_lshlrev_b32_e32 v127, 16, v88
	v_mul_f32_e32 v40, v40, v127
	v_and_b32_e32 v127, 0xffff0000, v88
	v_mul_f32_e32 v41, v41, v127
	v_lshlrev_b32_e32 v127, 16, v89
	v_mul_f32_e32 v42, v42, v127
	v_and_b32_e32 v127, 0xffff0000, v89
	v_mul_f32_e32 v43, v43, v127
	v_lshlrev_b32_e32 v127, 16, v90
	v_mul_f32_e32 v44, v44, v127
	v_and_b32_e32 v127, 0xffff0000, v90
	v_mul_f32_e32 v45, v45, v127
	v_lshlrev_b32_e32 v127, 16, v91
	v_mul_f32_e32 v46, v46, v127
	v_and_b32_e32 v127, 0xffff0000, v91
	v_mul_f32_e32 v47, v47, v127
	v_cvt_pk_bf16_f32 v40, v40, v41
	v_cvt_pk_bf16_f32 v41, v42, v43
	v_cvt_pk_bf16_f32 v42, v44, v45
	v_cvt_pk_bf16_f32 v43, v46, v47
	global_store_dwordx4 v125, v[40:43], s[96:97]
	v_add_u32_e32 v125, 0x4400, v125
	ds_read_b128 v[32:35], v119 offset:4352
	ds_read_b128 v[36:39], v119 offset:4368
	ds_read_b128 v[40:43], v119 offset:6528
	ds_read_b128 v[44:47], v119 offset:6544
	s_waitcnt vmcnt(3) lgkmcnt(2)
	v_lshlrev_b32_e32 v127, 16, v92
	v_mul_f32_e32 v32, v32, v127
	v_and_b32_e32 v127, 0xffff0000, v92
	v_mul_f32_e32 v33, v33, v127
	v_lshlrev_b32_e32 v127, 16, v93
	v_mul_f32_e32 v34, v34, v127
	v_and_b32_e32 v127, 0xffff0000, v93
	v_mul_f32_e32 v35, v35, v127
	v_lshlrev_b32_e32 v127, 16, v94
	v_mul_f32_e32 v36, v36, v127
	v_and_b32_e32 v127, 0xffff0000, v94
	v_mul_f32_e32 v37, v37, v127
	v_lshlrev_b32_e32 v127, 16, v95
	v_mul_f32_e32 v38, v38, v127
	v_and_b32_e32 v127, 0xffff0000, v95
	v_mul_f32_e32 v39, v39, v127
	v_cvt_pk_bf16_f32 v32, v32, v33
	v_cvt_pk_bf16_f32 v33, v34, v35
	v_cvt_pk_bf16_f32 v34, v36, v37
	v_cvt_pk_bf16_f32 v35, v38, v39
	global_store_dwordx4 v125, v[32:35], s[96:97]
	v_add_u32_e32 v125, 0x4400, v125
	s_waitcnt vmcnt(3) lgkmcnt(0)
	v_lshlrev_b32_e32 v127, 16, v96
	v_mul_f32_e32 v40, v40, v127
	v_and_b32_e32 v127, 0xffff0000, v96
	v_mul_f32_e32 v41, v41, v127
	v_lshlrev_b32_e32 v127, 16, v97
	v_mul_f32_e32 v42, v42, v127
	v_and_b32_e32 v127, 0xffff0000, v97
	v_mul_f32_e32 v43, v43, v127
	v_lshlrev_b32_e32 v127, 16, v98
	v_mul_f32_e32 v44, v44, v127
	v_and_b32_e32 v127, 0xffff0000, v98
	v_mul_f32_e32 v45, v45, v127
	v_lshlrev_b32_e32 v127, 16, v99
	v_mul_f32_e32 v46, v46, v127
	v_and_b32_e32 v127, 0xffff0000, v99
	v_mul_f32_e32 v47, v47, v127
	v_cvt_pk_bf16_f32 v40, v40, v41
	v_cvt_pk_bf16_f32 v41, v42, v43
	v_cvt_pk_bf16_f32 v42, v44, v45
	v_cvt_pk_bf16_f32 v43, v46, v47
	global_store_dwordx4 v125, v[40:43], s[96:97]
	v_add_u32_e32 v125, 0x4400, v125
	ds_write_b128 v118, v[16:19] offset:0
	ds_write_b128 v118, v[20:23] offset:32
	ds_write_b128 v118, v[24:27] offset:64
	ds_write_b128 v118, v[28:31] offset:96
	ds_write_b128 v118, v[0:3] offset:128
	ds_write_b128 v118, v[4:7] offset:160
	ds_write_b128 v118, v[8:11] offset:192
	ds_write_b128 v118, v[12:15] offset:224
	s_waitcnt lgkmcnt(0)
; __device__ __forceinline__ unsigned pk2(float lo, float hi) { f32v2_t v = {lo, hi}; bf16v2_t r = __builtin_convertvector(v, bf16v2_t); return __builtin_bit_cast(unsigned, r); }
; __device__ __forceinline__ float bflo(unsigned w) { return __uint_as_float(w << 16); }
; __device__ __forceinline__ float bfhi(unsigned w) { return __uint_as_float(w & 0xffff0000u); }
; __device__ void phase_merge(const Params& p, char* lds) {
;     ...
;     {
;       f32x16 acc[2][2]; zero_acc(acc);
;       gemm_mainloop<true>((const bf16_t*)(ws + W_C) + (size_t)m0 * LDH, LDH, (const bf16_t*)(ws + W_WA) + (size_t)n0 * LDH, LDH, 1024, acc, lds, 2 * ((mt + nt) & 7));
; #pragma unroll
;       for (int i = 0; i < 2; ++i)
; #pragma unroll
;         for (int j = 0; j < 2; ++j) {
;           const int tok = m0 + wr * 64 + i * 32 + l31; const int cb = n0 + wc * 64 + j * 32;
;           const bf16_t* gp = gates + (size_t)tok * 2048 + cb + 4 * hh;
;           bf16_t* op = mg + (size_t)tok * LDH + cb + 4 * hh;
; #pragma unroll
;           for (int g = 0; g < 4; ++g) {
;             const u32x2 gv = *(const u32x2*)(gp + 8 * g);
;             u32x2 w;
;             w.x = pk2(acc[i][j][4 * g] * bflo(gv.x), acc[i][j][4 * g + 1] * bfhi(gv.x));
;             w.y = pk2(acc[i][j][4 * g + 2] * bflo(gv.y), acc[i][j][4 * g + 3] * bfhi(gv.y));
;             *(u32x2*)(op + 8 * g) = w;
;           }
;         }
	global_load_dwordx4 v[84:87], v124, vcc offset:0
	v_add_u32_e32 v124, 0x8000, v124
	global_load_dwordx4 v[88:91], v124, vcc offset:0
	v_add_u32_e32 v124, 0x8000, v124
	global_load_dwordx4 v[92:95], v124, vcc offset:0
	v_add_u32_e32 v124, 0x8000, v124
	global_load_dwordx4 v[96:99], v124, vcc offset:0
	v_add_u32_e32 v124, 0x8000, v124
	ds_read_b128 v[0:3], v119 offset:0
	ds_read_b128 v[4:7], v119 offset:16
	ds_read_b128 v[8:11], v119 offset:2176
	ds_read_b128 v[12:15], v119 offset:2192
	s_waitcnt vmcnt(3) lgkmcnt(2)
	v_lshlrev_b32_e32 v127, 16, v84
	v_mul_f32_e32 v0, v0, v127
	v_and_b32_e32 v127, 0xffff0000, v84
	v_mul_f32_e32 v1, v1, v127
	v_lshlrev_b32_e32 v127, 16, v85
	v_mul_f32_e32 v2, v2, v127
	v_and_b32_e32 v127, 0xffff0000, v85
	v_mul_f32_e32 v3, v3, v127
	v_lshlrev_b32_e32 v127, 16, v86
	v_mul_f32_e32 v4, v4, v127
	v_and_b32_e32 v127, 0xffff0000, v86
	v_mul_f32_e32 v5, v5, v127
	v_lshlrev_b32_e32 v127, 16, v87
	v_mul_f32_e32 v6, v6, v127
	v_and_b32_e32 v127, 0xffff0000, v87
	v_mul_f32_e32 v7, v7, v127
	v_cvt_pk_bf16_f32 v0, v0, v1
	v_cvt_pk_bf16_f32 v1, v2, v3
	v_cvt_pk_bf16_f32 v2, v4, v5
	v_cvt_pk_bf16_f32 v3, v6, v7
	global_store_dwordx4 v125, v[0:3], s[96:97]
	v_add_u32_e32 v125, 0x4400, v125
	s_waitcnt vmcnt(3) lgkmcnt(0)
	v_lshlrev_b32_e32 v127, 16, v88
	v_mul_f32_e32 v8, v8, v127
	v_and_b32_e32 v127, 0xffff0000, v88
	v_mul_f32_e32 v9, v9, v127
	v_lshlrev_b32_e32 v127, 16, v89
	v_mul_f32_e32 v10, v10, v127
	v_and_b32_e32 v127, 0xffff0000, v89
	v_mul_f32_e32 v11, v11, v127
	v_lshlrev_b32_e32 v127, 16, v90
	v_mul_f32_e32 v12, v12, v127
	v_and_b32_e32 v127, 0xffff0000, v90
	v_mul_f32_e32 v13, v13, v127
	v_lshlrev_b32_e32 v127, 16, v91
	v_mul_f32_e32 v14, v14, v127
	v_and_b32_e32 v127, 0xffff0000, v91
	v_mul_f32_e32 v15, v15, v127
	v_cvt_pk_bf16_f32 v8, v8, v9
	v_cvt_pk_bf16_f32 v9, v10, v11
	v_cvt_pk_bf16_f32 v10, v12, v13
	v_cvt_pk_bf16_f32 v11, v14, v15
	global_store_dwordx4 v125, v[8:11], s[96:97]
	v_add_u32_e32 v125, 0x4400, v125
	ds_read_b128 v[0:3], v119 offset:4352
	ds_read_b128 v[4:7], v119 offset:4368
	ds_read_b128 v[8:11], v119 offset:6528
	ds_read_b128 v[12:15], v119 offset:6544
	s_waitcnt vmcnt(3) lgkmcnt(2)
	v_lshlrev_b32_e32 v127, 16, v92
	v_mul_f32_e32 v0, v0, v127
	v_and_b32_e32 v127, 0xffff0000, v92
	v_mul_f32_e32 v1, v1, v127
	v_lshlrev_b32_e32 v127, 16, v93
	v_mul_f32_e32 v2, v2, v127
	v_and_b32_e32 v127, 0xffff0000, v93
	v_mul_f32_e32 v3, v3, v127
	v_lshlrev_b32_e32 v127, 16, v94
	v_mul_f32_e32 v4, v4, v127
	v_and_b32_e32 v127, 0xffff0000, v94
	v_mul_f32_e32 v5, v5, v127
	v_lshlrev_b32_e32 v127, 16, v95
	v_mul_f32_e32 v6, v6, v127
	v_and_b32_e32 v127, 0xffff0000, v95
	v_mul_f32_e32 v7, v7, v127
	v_cvt_pk_bf16_f32 v0, v0, v1
	v_cvt_pk_bf16_f32 v1, v2, v3
	v_cvt_pk_bf16_f32 v2, v4, v5
	v_cvt_pk_bf16_f32 v3, v6, v7
	global_store_dwordx4 v125, v[0:3], s[96:97]
	v_add_u32_e32 v125, 0x4400, v125
	s_waitcnt vmcnt(3) lgkmcnt(0)
; __device__ __forceinline__ unsigned pk2(float lo, float hi) { f32v2_t v = {lo, hi}; bf16v2_t r = __builtin_convertvector(v, bf16v2_t); return __builtin_bit_cast(unsigned, r); }
; __device__ __forceinline__ float bflo(unsigned w) { return __uint_as_float(w << 16); }
; __device__ __forceinline__ float bfhi(unsigned w) { return __uint_as_float(w & 0xffff0000u); }
; template <bool SW>
; __device__ __forceinline__ void gemm_mainloop(const bf16_t* __restrict__ A, int lda, const bf16_t* __restrict__ Bt, int ldb, int K,
;                                               f32x16 (&acc)[2][2], char* lds, int kstart) {
;     ...
;   const bf16_t* ap[4]; const bf16_t* bp[4];
; #pragma unroll
;   for (int i = 0; i < 4; ++i) {
;     const int row = lrow + 8 * i; const int ch = (lane & 7) ^ ((row >> 1) & 7);
;     ap[i] = A + (size_t)row * lda + ch * 8; bp[i] = Bt + (size_t)row * ldb + ch * 8;
;   }
;   char* ldst = lds + (wid * 32) * 128 + lane * 16;
; #pragma unroll
;   for (int i = 0; i < 4; ++i) { glds16(ap[i] + kstart * 64, ldst + i * 1024); glds16(bp[i] + kstart * 64, ldst + 16384 + i * 1024); }
;   asm volatile("s_waitcnt vmcnt(0)" ::: "memory");
;   __syncthreads();
; __device__ void phase_merge(const Params& p, char* lds) {
;     ...
;             const u32x2 gv = *(const u32x2*)(gp + 8 * g);
;             u32x2 w;
;             w.x = pk2(acc[i][j][4 * g] * bflo(gv.x), acc[i][j][4 * g + 1] * bfhi(gv.x));
;             w.y = pk2(acc[i][j][4 * g + 2] * bflo(gv.y), acc[i][j][4 * g + 3] * bfhi(gv.y));
;             *(u32x2*)(op + 8 * g) = w;
;           }
;         }
	v_lshlrev_b32_e32 v127, 16, v96
	v_mul_f32_e32 v8, v8, v127
	v_and_b32_e32 v127, 0xffff0000, v96
	v_mul_f32_e32 v9, v9, v127
	v_lshlrev_b32_e32 v127, 16, v97
	v_mul_f32_e32 v10, v10, v127
	v_and_b32_e32 v127, 0xffff0000, v97
	v_mul_f32_e32 v11, v11, v127
	v_lshlrev_b32_e32 v127, 16, v98
	v_mul_f32_e32 v12, v12, v127
	v_and_b32_e32 v127, 0xffff0000, v98
	v_mul_f32_e32 v13, v13, v127
	v_lshlrev_b32_e32 v127, 16, v99
	v_mul_f32_e32 v14, v14, v127
	v_and_b32_e32 v127, 0xffff0000, v99
	v_mul_f32_e32 v15, v15, v127
	v_cvt_pk_bf16_f32 v8, v8, v9
	v_cvt_pk_bf16_f32 v9, v10, v11
	v_cvt_pk_bf16_f32 v10, v12, v13
	v_cvt_pk_bf16_f32 v11, v14, v15
	global_store_dwordx4 v125, v[8:11], s[96:97]
	v_add_u32_e32 v125, 0x4400, v125
	v_mov_b32_e32 v77, v65
	v_mov_b32_e32 v79, v65
	s_add_u32 s0, s24, s38
	s_addc_u32 s1, s25, s39
	s_add_u32 s38, s26, s40
	s_addc_u32 s39, s27, s41
	s_lshl_b32 s10, s43, 1
	v_lshl_add_u64 v[0:1], s[0:1], 0, v[64:65]
	v_lshl_add_u64 v[86:87], v[0:1], 0, v[76:77]
	v_lshl_add_u64 v[0:1], s[38:39], 0, v[64:65]
	v_lshl_add_u64 v[88:89], v[0:1], 0, v[76:77]
	v_lshl_add_u64 v[0:1], s[0:1], 0, v[70:71]
	v_lshl_add_u64 v[90:91], v[0:1], 0, v[78:79]
	v_lshl_add_u64 v[0:1], s[38:39], 0, v[70:71]
	v_lshl_add_u64 v[92:93], v[0:1], 0, v[78:79]
	v_lshl_add_u64 v[0:1], s[0:1], 0, v[72:73]
	v_lshl_add_u64 v[94:95], v[0:1], 0, v[76:77]
	v_lshl_add_u64 v[0:1], s[38:39], 0, v[72:73]
	v_lshl_add_u64 v[96:97], v[0:1], 0, v[76:77]
	v_lshl_add_u64 v[0:1], s[0:1], 0, v[74:75]
	v_lshl_add_u64 v[98:99], v[0:1], 0, v[78:79]
	v_lshl_add_u64 v[0:1], s[38:39], 0, v[74:75]
	v_readfirstlane_b32 s0, v102
	v_lshl_add_u64 v[100:101], v[0:1], 0, v[78:79]
	v_lshl_add_u64 v[0:1], v[86:87], 0, s[10:11]
	s_mov_b32 m0, s0
	v_readfirstlane_b32 s0, v111
	global_load_lds_dwordx4 v[0:1], off
	v_lshl_add_u64 v[0:1], v[88:89], 0, s[10:11]
	s_mov_b32 m0, s0
	v_readfirstlane_b32 s0, v112
	global_load_lds_dwordx4 v[0:1], off
	v_lshl_add_u64 v[0:1], v[90:91], 0, s[10:11]
	s_mov_b32 m0, s0
	v_readfirstlane_b32 s0, v113
	global_load_lds_dwordx4 v[0:1], off
	v_lshl_add_u64 v[0:1], v[92:93], 0, s[10:11]
	s_mov_b32 m0, s0
	v_readfirstlane_b32 s0, v114
	global_load_lds_dwordx4 v[0:1], off
	v_lshl_add_u64 v[0:1], v[94:95], 0, s[10:11]
	s_mov_b32 m0, s0
	v_readfirstlane_b32 s0, v115
	global_load_lds_dwordx4 v[0:1], off
	v_lshl_add_u64 v[0:1], v[96:97], 0, s[10:11]
	s_mov_b32 m0, s0
	v_readfirstlane_b32 s0, v116
	global_load_lds_dwordx4 v[0:1], off
	v_lshl_add_u64 v[0:1], v[98:99], 0, s[10:11]
	s_mov_b32 m0, s0
	v_readfirstlane_b32 s0, v117
	global_load_lds_dwordx4 v[0:1], off
	v_lshl_add_u64 v[0:1], v[100:101], 0, s[10:11]
	s_mov_b32 m0, s0
	s_mov_b32 s39, 0
	global_load_lds_dwordx4 v[0:1], off
	s_waitcnt vmcnt(0)
	v_mov_b32_e32 v0, 0
	s_mov_b32 s38, 0
	v_mov_b32_e32 v1, v0
	v_mov_b32_e32 v2, v0
	v_mov_b32_e32 v3, v0
	v_mov_b32_e32 v4, v0
	v_mov_b32_e32 v5, v0
	v_mov_b32_e32 v6, v0
	v_mov_b32_e32 v7, v0
	v_mov_b32_e32 v8, v0
	v_mov_b32_e32 v9, v0
	v_mov_b32_e32 v10, v0
	v_mov_b32_e32 v11, v0
	v_mov_b32_e32 v12, v0
	v_mov_b32_e32 v13, v0
	v_mov_b32_e32 v14, v0
	v_mov_b32_e32 v15, v0
	v_mov_b32_e32 v16, v0
	v_mov_b32_e32 v17, v0
	v_mov_b32_e32 v18, v0
	v_mov_b32_e32 v19, v0
	v_mov_b32_e32 v20, v0
	v_mov_b32_e32 v21, v0
	v_mov_b32_e32 v22, v0
	v_mov_b32_e32 v23, v0
	v_mov_b32_e32 v24, v0
	v_mov_b32_e32 v25, v0
	v_mov_b32_e32 v26, v0
	v_mov_b32_e32 v27, v0
	v_mov_b32_e32 v28, v0
	v_mov_b32_e32 v29, v0
	v_mov_b32_e32 v30, v0
	v_mov_b32_e32 v31, v0
	v_mov_b32_e32 v32, v0
	v_mov_b32_e32 v33, v0
	v_mov_b32_e32 v34, v0
	v_mov_b32_e32 v35, v0
	v_mov_b32_e32 v36, v0
	v_mov_b32_e32 v37, v0
	v_mov_b32_e32 v38, v0
	v_mov_b32_e32 v39, v0
	v_mov_b32_e32 v40, v0
	v_mov_b32_e32 v41, v0
	v_mov_b32_e32 v42, v0
	v_mov_b32_e32 v43, v0
	v_mov_b32_e32 v44, v0
	v_mov_b32_e32 v45, v0
	v_mov_b32_e32 v46, v0
	v_mov_b32_e32 v47, v0
	v_mov_b32_e32 v48, v0
	v_mov_b32_e32 v49, v0
	v_mov_b32_e32 v50, v0
	v_mov_b32_e32 v51, v0
	v_mov_b32_e32 v52, v0
	v_mov_b32_e32 v53, v0
	v_mov_b32_e32 v54, v0
	v_mov_b32_e32 v55, v0
	v_mov_b32_e32 v56, v0
	v_mov_b32_e32 v57, v0
	v_mov_b32_e32 v58, v0
	v_mov_b32_e32 v59, v0
	v_mov_b32_e32 v60, v0
	v_mov_b32_e32 v61, v0
	v_mov_b32_e32 v62, v0
	v_mov_b32_e32 v63, v0
	s_waitcnt vmcnt(0) lgkmcnt(0)
	s_barrier
	s_branch .LBB0_796

; __device__ void phase_outproj(const Params& p, char* lds) {
;     ...
; #pragma unroll
;     for (int i = 0; i < 2; ++i)
; #pragma unroll
;       for (int j = 0; j < 2; ++j) {
;         const int tok = m0 + wr * 64 + i * 32 + l31; const int cb = n0 + wc * 64 + j * 32 + 4 * hh;
;         const float* xr = ((tok < TP) ? p.in[0] + (size_t)tok * 1024 : p.in[1] + (size_t)(tok - TP) * 1024) + cb;
;         float* orow = x1 + (size_t)tok * 1024 + cb;
; #pragma unroll
;         for (int g = 0; g < 4; ++g) {
;           const f32x4 xv = *(const f32x4*)(xr + 8 * g);
;           f32x4 w = {xv[0] + acc[i][j][4 * g], xv[1] + acc[i][j][4 * g + 1], xv[2] + acc[i][j][4 * g + 2], xv[3] + acc[i][j][4 * g + 3]};
;           *(f32x4*)(orow + 8 * g) = w;
;         }
;       }
.LBB0_869:
	v_and_b32_e32 v117, 63, v181
	v_lshrrev_b32_e32 v116, 6, v181
	v_and_b32_e32 v112, 31, v117
	v_lshrrev_b32_e32 v113, 5, v117
	v_mul_u32_u24_e32 v112, 0x110, v112
	v_lshlrev_b32_e32 v113, 4, v113
	v_mul_u32_u24_e32 v114, 0x2200, v116
	v_add3_u32 v112, v112, v113, v114
	v_add_u32_e32 v112, 0x8000, v112
	v_add_u32_e32 v113, 0x8000, v114
	v_lshrrev_b32_e32 v114, 4, v117
	v_and_b32_e32 v115, 15, v117
	v_mul_u32_u24_e32 v117, 0x110, v114
	v_add_u32_e32 v113, v113, v117
	v_lshl_add_u32 v113, v115, 4, v113
	s_cmp_lt_i32 s3, 0x8000
	s_cselect_b32 vcc_lo, s52, s54
	s_cselect_b32 vcc_hi, s53, s55
	s_cselect_b32 s0, 0, 0x8000
	s_sub_i32 s0, s3, s0
	s_lshl_b32 s0, s0, 12
	s_lshl_b32 s12, s38, 2
	s_add_i32 s0, s0, s12
	s_lshl_b32 s1, s3, 12
	s_add_i32 s1, s1, s12
	s_add_i32 s1, s1, 0xa08e000
	v_lshrrev_b32_e32 v118, 1, v116
	v_mul_u32_u24_e32 v118, 0x40000, v118
	v_mul_u32_u24_e32 v120, 0x1000, v114
	v_add_u32_e32 v118, v118, v120
	v_and_b32_e32 v120, 1, v116
	v_mul_u32_u24_e32 v120, 0x100, v120
	v_lshl_add_u32 v120, v115, 4, v120
	v_add3_u32 v118, v118, v120, s0
	v_lshrrev_b32_e32 v119, 1, v116
	v_mul_u32_u24_e32 v119, 0x40000, v119
	v_mul_u32_u24_e32 v120, 0x1000, v114
	v_add_u32_e32 v119, v119, v120
	v_and_b32_e32 v120, 1, v116
	v_mul_u32_u24_e32 v120, 0x100, v120
	v_lshl_add_u32 v120, v115, 4, v120
	v_add3_u32 v119, v119, v120, s1
	ds_write_b128 v112, v[48:51] offset:0
	ds_write_b128 v112, v[52:55] offset:32
	ds_write_b128 v112, v[56:59] offset:64
	ds_write_b128 v112, v[60:63] offset:96
	ds_write_b128 v112, v[32:35] offset:128
	ds_write_b128 v112, v[36:39] offset:160
	ds_write_b128 v112, v[40:43] offset:192
	ds_write_b128 v112, v[44:47] offset:224
	s_waitcnt lgkmcnt(0)
	global_load_dwordx4 v[80:83], v118, vcc
	v_add_u32_e32 v118, 0x4000, v118
	global_load_dwordx4 v[84:87], v118, vcc
	v_add_u32_e32 v118, 0x4000, v118
	global_load_dwordx4 v[88:91], v118, vcc
	v_add_u32_e32 v118, 0x4000, v118
	global_load_dwordx4 v[92:95], v118, vcc
	v_add_u32_e32 v118, 0x4000, v118
	ds_read_b128 v[32:35], v113 offset:0
	ds_read_b128 v[36:39], v113 offset:1088
	ds_read_b128 v[40:43], v113 offset:2176
	ds_read_b128 v[44:47], v113 offset:3264
	s_waitcnt vmcnt(3) lgkmcnt(3)
	v_add_f32_e32 v32, v32, v80
	v_add_f32_e32 v33, v33, v81
	v_add_f32_e32 v34, v34, v82
	v_add_f32_e32 v35, v35, v83
	global_store_dwordx4 v119, v[32:35], s[96:97]
	v_add_u32_e32 v119, 0x4000, v119
	s_waitcnt vmcnt(3) lgkmcnt(2)
	v_add_f32_e32 v36, v36, v84
	v_add_f32_e32 v37, v37, v85
	v_add_f32_e32 v38, v38, v86
	v_add_f32_e32 v39, v39, v87
	global_store_dwordx4 v119, v[36:39], s[96:97]
	v_add_u32_e32 v119, 0x4000, v119
	s_waitcnt vmcnt(3) lgkmcnt(1)
	v_add_f32_e32 v40, v40, v88
	v_add_f32_e32 v41, v41, v89
	v_add_f32_e32 v42, v42, v90
	v_add_f32_e32 v43, v43, v91
	global_store_dwordx4 v119, v[40:43], s[96:97]
	v_add_u32_e32 v119, 0x4000, v119
	s_waitcnt vmcnt(3) lgkmcnt(0)
	v_add_f32_e32 v44, v44, v92
	v_add_f32_e32 v45, v45, v93
	v_add_f32_e32 v46, v46, v94
	v_add_f32_e32 v47, v47, v95
	global_store_dwordx4 v119, v[44:47], s[96:97]
	v_add_u32_e32 v119, 0x4000, v119
	global_load_dwordx4 v[80:83], v118, vcc
	v_add_u32_e32 v118, 0x4000, v118
	global_load_dwordx4 v[84:87], v118, vcc
	v_add_u32_e32 v118, 0x4000, v118
	global_load_dwordx4 v[88:91], v118, vcc
	v_add_u32_e32 v118, 0x4000, v118
	global_load_dwordx4 v[92:95], v118, vcc
	v_add_u32_e32 v118, 0x4000, v118
	ds_read_b128 v[32:35], v113 offset:4352
	ds_read_b128 v[36:39], v113 offset:5440
	ds_read_b128 v[40:43], v113 offset:6528
	ds_read_b128 v[44:47], v113 offset:7616
	s_waitcnt vmcnt(3) lgkmcnt(3)
	v_add_f32_e32 v32, v32, v80
	v_add_f32_e32 v33, v33, v81
	v_add_f32_e32 v34, v34, v82
	v_add_f32_e32 v35, v35, v83
	global_store_dwordx4 v119, v[32:35], s[96:97]
	v_add_u32_e32 v119, 0x4000, v119
	s_waitcnt vmcnt(3) lgkmcnt(2)
; __device__ void phase_outproj(const Params& p, char* lds) {
;     ...
; #pragma unroll
;     for (int i = 0; i < 2; ++i)
; #pragma unroll
;       for (int j = 0; j < 2; ++j) {
;         const int tok = m0 + wr * 64 + i * 32 + l31; const int cb = n0 + wc * 64 + j * 32 + 4 * hh;
;         const float* xr = ((tok < TP) ? p.in[0] + (size_t)tok * 1024 : p.in[1] + (size_t)(tok - TP) * 1024) + cb;
;         float* orow = x1 + (size_t)tok * 1024 + cb;
; #pragma unroll
;         for (int g = 0; g < 4; ++g) {
;           const f32x4 xv = *(const f32x4*)(xr + 8 * g);
;           f32x4 w = {xv[0] + acc[i][j][4 * g], xv[1] + acc[i][j][4 * g + 1], xv[2] + acc[i][j][4 * g + 2], xv[3] + acc[i][j][4 * g + 3]};
;           *(f32x4*)(orow + 8 * g) = w;
;         }
;       }
	v_add_f32_e32 v36, v36, v84
	v_add_f32_e32 v37, v37, v85
	v_add_f32_e32 v38, v38, v86
	v_add_f32_e32 v39, v39, v87
	global_store_dwordx4 v119, v[36:39], s[96:97]
	v_add_u32_e32 v119, 0x4000, v119
	s_waitcnt vmcnt(3) lgkmcnt(1)
	v_add_f32_e32 v40, v40, v88
	v_add_f32_e32 v41, v41, v89
	v_add_f32_e32 v42, v42, v90
	v_add_f32_e32 v43, v43, v91
	global_store_dwordx4 v119, v[40:43], s[96:97]
	v_add_u32_e32 v119, 0x4000, v119
	s_waitcnt vmcnt(3) lgkmcnt(0)
	v_add_f32_e32 v44, v44, v92
	v_add_f32_e32 v45, v45, v93
	v_add_f32_e32 v46, v46, v94
	v_add_f32_e32 v47, v47, v95
	global_store_dwordx4 v119, v[44:47], s[96:97]
	v_add_u32_e32 v119, 0x4000, v119
	ds_write_b128 v112, v[16:19] offset:0
	ds_write_b128 v112, v[20:23] offset:32
	ds_write_b128 v112, v[24:27] offset:64
	ds_write_b128 v112, v[28:31] offset:96
	ds_write_b128 v112, v[0:3] offset:128
	ds_write_b128 v112, v[4:7] offset:160
	ds_write_b128 v112, v[8:11] offset:192
	ds_write_b128 v112, v[12:15] offset:224
	s_waitcnt lgkmcnt(0)
	global_load_dwordx4 v[80:83], v118, vcc
	v_add_u32_e32 v118, 0x4000, v118
	global_load_dwordx4 v[84:87], v118, vcc
	v_add_u32_e32 v118, 0x4000, v118
	global_load_dwordx4 v[88:91], v118, vcc
	v_add_u32_e32 v118, 0x4000, v118
	global_load_dwordx4 v[92:95], v118, vcc
	v_add_u32_e32 v118, 0x4000, v118
	ds_read_b128 v[0:3], v113 offset:0
	ds_read_b128 v[4:7], v113 offset:1088
	ds_read_b128 v[8:11], v113 offset:2176
	ds_read_b128 v[12:15], v113 offset:3264
	s_waitcnt vmcnt(3) lgkmcnt(3)
	v_add_f32_e32 v0, v0, v80
	v_add_f32_e32 v1, v1, v81
	v_add_f32_e32 v2, v2, v82
	v_add_f32_e32 v3, v3, v83
	global_store_dwordx4 v119, v[0:3], s[96:97]
	v_add_u32_e32 v119, 0x4000, v119
	s_waitcnt vmcnt(3) lgkmcnt(2)
	v_add_f32_e32 v4, v4, v84
	v_add_f32_e32 v5, v5, v85
	v_add_f32_e32 v6, v6, v86
	v_add_f32_e32 v7, v7, v87
	global_store_dwordx4 v119, v[4:7], s[96:97]
	v_add_u32_e32 v119, 0x4000, v119
	s_waitcnt vmcnt(3) lgkmcnt(1)
	v_add_f32_e32 v8, v8, v88
	v_add_f32_e32 v9, v9, v89
	v_add_f32_e32 v10, v10, v90
	v_add_f32_e32 v11, v11, v91
	global_store_dwordx4 v119, v[8:11], s[96:97]
	v_add_u32_e32 v119, 0x4000, v119
	s_waitcnt vmcnt(3) lgkmcnt(0)
	v_add_f32_e32 v12, v12, v92
	v_add_f32_e32 v13, v13, v93
	v_add_f32_e32 v14, v14, v94
	v_add_f32_e32 v15, v15, v95
	global_store_dwordx4 v119, v[12:15], s[96:97]
	v_add_u32_e32 v119, 0x4000, v119
	global_load_dwordx4 v[80:83], v118, vcc
	v_add_u32_e32 v118, 0x4000, v118
	global_load_dwordx4 v[84:87], v118, vcc
	v_add_u32_e32 v118, 0x4000, v118
	global_load_dwordx4 v[88:91], v118, vcc
	v_add_u32_e32 v118, 0x4000, v118
	global_load_dwordx4 v[92:95], v118, vcc
	v_add_u32_e32 v118, 0x4000, v118
	ds_read_b128 v[0:3], v113 offset:4352
	ds_read_b128 v[4:7], v113 offset:5440
	ds_read_b128 v[8:11], v113 offset:6528
	ds_read_b128 v[12:15], v113 offset:7616
	s_waitcnt vmcnt(3) lgkmcnt(3)
	v_add_f32_e32 v0, v0, v80
	v_add_f32_e32 v1, v1, v81
	v_add_f32_e32 v2, v2, v82
	v_add_f32_e32 v3, v3, v83
	global_store_dwordx4 v119, v[0:3], s[96:97]
	v_add_u32_e32 v119, 0x4000, v119
	s_waitcnt vmcnt(3) lgkmcnt(2)
	v_add_f32_e32 v4, v4, v84
	v_add_f32_e32 v5, v5, v85
	v_add_f32_e32 v6, v6, v86
	v_add_f32_e32 v7, v7, v87
	global_store_dwordx4 v119, v[4:7], s[96:97]
	v_add_u32_e32 v119, 0x4000, v119
	s_waitcnt vmcnt(3) lgkmcnt(1)
	v_add_f32_e32 v8, v8, v88
	v_add_f32_e32 v9, v9, v89
	v_add_f32_e32 v10, v10, v90
	v_add_f32_e32 v11, v11, v91
	global_store_dwordx4 v119, v[8:11], s[96:97]
	v_add_u32_e32 v119, 0x4000, v119
	s_waitcnt vmcnt(3) lgkmcnt(0)
	v_add_f32_e32 v12, v12, v92
	v_add_f32_e32 v13, v13, v93
	v_add_f32_e32 v14, v14, v94
	v_add_f32_e32 v15, v15, v95
	global_store_dwordx4 v119, v[12:15], s[96:97]
	v_add_u32_e32 v119, 0x4000, v119
	s_add_i32 s2, s2, 1
	s_mul_i32 s0, s2, s18
	s_add_i32 s0, s0, s17
	s_cmp_lt_i32 s0, s72
	s_cbranch_scc0 .LBB0_876
